# baseline (speedup 1.0000x reference)
;   __device__ __forceinline__ u16* hbuf() const { return (u16*)(ws + 57 * MB); }
; #define WAIT_V(n) asm volatile("s_waitcnt vmcnt(%0)" ::"n"(n) : "memory")
; #define WAIT_L(n) asm volatile("s_waitcnt lgkmcnt(%0)" ::"n"(n) : "memory")
; #define BAR8 __builtin_amdgcn_s_barrier()
; template <int EPI> ...
;     ...
;       bf16x8 At[4][2], B0[2][2], B1[2][2];
;       if (wr == 1) BAR8;
;       BAR8;
;       STAGE_Bm(1, 0, Bb, 1); STAGE_A(1, 0, Ab, 1); STAGE_Bm(1, 1, Bb, 1);
;       WAIT_V(6); BAR8;
; #pragma unroll 1
;       for (int t0_ = 0; t0_ < nt - 2; t0_ += 2) {
;         if constexpr (EPI == EPI_M0) {
;           if (t0_ == 8) {
;             int tid_s = tid;
;             asm volatile("" : "+v"(tid_s));
;             const int wid = tid_s >> 6, lane = tid_s & 63, wr = wid >> 2, wc = wid & 3, fr = lane & 15, fq = lane >> 4;
;             char* wsn = shm + 131072 + wid * 4096;
;             u16* sout = p.hbuf() + (long)(pm * 256 + wr * 128 + (lane >> 3)) * DM + pn * 256 + wc * 64 + (lane & 7) * 8;
; #pragma unroll
;             for (int qd = 0; qd < 4; ++qd) {
; #pragma unroll
;               for (int mm = 0; mm < 2; ++mm)
; #pragma unroll
;                 for (int n = 0; n < 4; ++n) {
;                   const f32x4 v = acc[qd * 2 + mm][n];
;                   u32x2 o = {pack2(v[0], v[1]), pack2(v[2], v[3])};
;                   *(u32x2*)(wsn + (mm * 16 + fr) * 128 + (((n * 2 + (fq >> 1)) ^ (fr & 7)) << 4) + (fq & 1) * 8) = o;
;                 }
;               asm volatile("s_waitcnt lgkmcnt(0)" ::: "memory");
; #pragma unroll
;               for (int i = 0; i < 4; ++i) {
;                 const u32x4 d = *(const u32x4*)(wsn + (i * 8 + (lane >> 3)) * 128 + (((lane & 7) ^ ((lane >> 3) & 7)) << 4));
;                 *(u32x4*)(sout + (long)(qd * 32 + i * 8) * DM) = d;
;               }
;               asm volatile("s_waitcnt lgkmcnt(0)" ::: "memory");
;             }
;           }
;         }
;         int t = t0_;
;         asm volatile("" : "+s"(t));
;         LDB8(B0, 0, 0); SCHED8; LDA8(At, 0, 0); STAGE_A(1, 1, Ab, t + 1);
;         WAIT_L(8); BAR8; WAIT_L(0); MMA8(0, 0, At, B0); BAR8; SCHED8;
;         LDB8(B1, 0, 1); STAGE_Bm(0, 0, Bb, t + 2);
;         BAR8; WAIT_L(0); MMA8(0, 1, At, B1); BAR8;
;         LDA8(At, 0, 1); STAGE_A(0, 0, Ab, t + 2);
;         BAR8; WAIT_L(0); MMA8(1, 0, At, B0); BAR8; SCHED8;
.LBB0_683:
	v_lshl_add_u64 v[172:173], s[22:23], 0, v[4:5]
	v_lshl_add_u64 v[170:171], s[24:25], 0, v[0:1]
	s_mov_b64 s[22:23], 0x20000
	v_lshl_add_u64 v[174:175], v[170:171], 0, s[22:23]
	v_lshl_add_u64 v[176:177], v[172:173], 0, s[44:45]
	v_add_u32_e32 v180, 0x10000, v7
	v_add_u32_e32 v181, 0x10000, v153
	s_mov_b64 s[22:23], 0x80
	s_add_i32 m0, s96, 0x10000
	v_lshl_add_u64 v[178:179], v[170:171], 0, s[22:23]
	global_load_lds_dwordx4 v[178:179], off
	s_add_i32 m0, s96, 0x12000
	v_lshl_add_u64 v[178:179], v[170:171], 0, s[22:23]
	v_lshl_add_u64 v[178:179], v[178:179], 0, s[62:63]
	global_load_lds_dwordx4 v[178:179], off
	s_add_i32 m0, s96, 0x14000
	v_lshl_add_u64 v[178:179], v[174:175], 0, s[22:23]
	global_load_lds_dwordx4 v[178:179], off
	s_add_i32 m0, s96, 0x16000
	v_lshl_add_u64 v[178:179], v[174:175], 0, s[22:23]
	v_lshl_add_u64 v[178:179], v[178:179], 0, s[62:63]
	global_load_lds_dwordx4 v[178:179], off
	s_add_i32 m0, s96, 0x18000
	v_lshl_add_u64 v[178:179], v[172:173], 0, s[22:23]
	global_load_lds_dwordx4 v[178:179], off
	s_add_i32 m0, s96, 0x1a000
	v_lshl_add_u64 v[178:179], v[172:173], 0, s[22:23]
	v_lshl_add_u64 v[178:179], v[178:179], 0, s[62:63]
	global_load_lds_dwordx4 v[178:179], off
	s_add_i32 m0, s96, 0x1c000
	v_lshl_add_u64 v[178:179], v[176:177], 0, s[22:23]
	global_load_lds_dwordx4 v[178:179], off
	s_add_i32 m0, s96, 0x1e000
	v_lshl_add_u64 v[178:179], v[176:177], 0, s[22:23]
	v_lshl_add_u64 v[178:179], v[178:179], 0, s[62:63]
	global_load_lds_dwordx4 v[178:179], off
	ds_read_b128 v[186:189], v153 offset:32768
	ds_read_b128 v[190:193], v153 offset:34816
	ds_read_b128 v[218:221], v7
	ds_read_b128 v[194:197], v153 offset:49152
	ds_read_b128 v[198:201], v153 offset:51200
	ds_read_b128 v[222:225], v7 offset:2048
	ds_read_b128 v[226:229], v7 offset:4096
	ds_read_b128 v[230:233], v7 offset:6144
	ds_read_b128 v[234:237], v7 offset:16384
	s_waitcnt lgkmcnt(4)
	v_mfma_f32_16x16x32_bf16 v[132:135], v[186:189], v[218:221], 0
	v_mfma_f32_16x16x32_bf16 v[124:127], v[190:193], v[218:221], 0
	v_mfma_f32_16x16x32_bf16 v[128:131], v[194:197], v[218:221], 0
	v_mfma_f32_16x16x32_bf16 v[120:123], v[198:201], v[218:221], 0
	ds_read_b128 v[238:241], v7 offset:18432
	ds_read_b128 v[202:205], v153 offset:33792
	s_waitcnt lgkmcnt(5)
	v_mfma_f32_16x16x32_bf16 v[116:119], v[186:189], v[222:225], 0
	v_mfma_f32_16x16x32_bf16 v[108:111], v[190:193], v[222:225], 0
	v_mfma_f32_16x16x32_bf16 v[112:115], v[194:197], v[222:225], 0
	v_mfma_f32_16x16x32_bf16 v[104:107], v[198:201], v[222:225], 0
	ds_read_b128 v[242:245], v7 offset:20480
	ds_read_b128 v[206:209], v153 offset:35840
	s_waitcnt lgkmcnt(6)
	v_mfma_f32_16x16x32_bf16 v[100:103], v[186:189], v[226:229], 0
	v_mfma_f32_16x16x32_bf16 v[92:95], v[190:193], v[226:229], 0
	v_mfma_f32_16x16x32_bf16 v[96:99], v[194:197], v[226:229], 0
	v_mfma_f32_16x16x32_bf16 v[88:91], v[198:201], v[226:229], 0
	ds_read_b128 v[246:249], v7 offset:22528
	ds_read_b128 v[210:213], v153 offset:50176
	s_waitcnt lgkmcnt(7)
	v_mfma_f32_16x16x32_bf16 v[84:87], v[186:189], v[230:233], 0
	v_mfma_f32_16x16x32_bf16 v[76:79], v[190:193], v[230:233], 0
	v_mfma_f32_16x16x32_bf16 v[80:83], v[194:197], v[230:233], 0
	v_mfma_f32_16x16x32_bf16 v[72:75], v[198:201], v[230:233], 0
	ds_read_b128 v[218:221], v7 offset:1024
	ds_read_b128 v[214:217], v153 offset:52224
	s_add_u32 s22, s22, 0x80
	s_waitcnt lgkmcnt(8)
	v_mfma_f32_16x16x32_bf16 v[68:71], v[186:189], v[234:237], 0
	v_mfma_f32_16x16x32_bf16 v[64:67], v[190:193], v[234:237], 0
	v_mfma_f32_16x16x32_bf16 v[60:63], v[194:197], v[234:237], 0
	v_mfma_f32_16x16x32_bf16 v[56:59], v[198:201], v[234:237], 0
	ds_read_b128 v[222:225], v7 offset:3072
	s_waitcnt lgkmcnt(8)
	v_mfma_f32_16x16x32_bf16 v[52:55], v[186:189], v[238:241], 0
	v_mfma_f32_16x16x32_bf16 v[48:51], v[190:193], v[238:241], 0
	v_mfma_f32_16x16x32_bf16 v[44:47], v[194:197], v[238:241], 0
	v_mfma_f32_16x16x32_bf16 v[40:43], v[198:201], v[238:241], 0
	ds_read_b128 v[226:229], v7 offset:5120
	s_waitcnt lgkmcnt(7)
	v_mfma_f32_16x16x32_bf16 v[36:39], v[186:189], v[242:245], 0
	v_mfma_f32_16x16x32_bf16 v[32:35], v[190:193], v[242:245], 0
	v_mfma_f32_16x16x32_bf16 v[28:31], v[194:197], v[242:245], 0
	v_mfma_f32_16x16x32_bf16 v[24:27], v[198:201], v[242:245], 0
	ds_read_b128 v[230:233], v7 offset:7168
	s_waitcnt lgkmcnt(6)
	v_mfma_f32_16x16x32_bf16 v[20:23], v[186:189], v[246:249], 0
	v_mfma_f32_16x16x32_bf16 v[16:19], v[190:193], v[246:249], 0
	v_mfma_f32_16x16x32_bf16 v[12:15], v[194:197], v[246:249], 0
	v_mfma_f32_16x16x32_bf16 v[8:11], v[198:201], v[246:249], 0
	ds_read_b128 v[234:237], v7 offset:17408
	s_waitcnt lgkmcnt(4)
	v_mfma_f32_16x16x32_bf16 v[132:135], v[202:205], v[218:221], v[132:135]
	v_mfma_f32_16x16x32_bf16 v[124:127], v[206:209], v[218:221], v[124:127]
	v_mfma_f32_16x16x32_bf16 v[128:131], v[210:213], v[218:221], v[128:131]
	v_mfma_f32_16x16x32_bf16 v[120:123], v[214:217], v[218:221], v[120:123]
	ds_read_b128 v[238:241], v7 offset:19456
	s_waitcnt lgkmcnt(4)
	v_mfma_f32_16x16x32_bf16 v[116:119], v[202:205], v[222:225], v[116:119]
	v_mfma_f32_16x16x32_bf16 v[108:111], v[206:209], v[222:225], v[108:111]
	v_mfma_f32_16x16x32_bf16 v[112:115], v[210:213], v[222:225], v[112:115]
	v_mfma_f32_16x16x32_bf16 v[104:107], v[214:217], v[222:225], v[104:107]
	ds_read_b128 v[242:245], v7 offset:21504
	s_waitcnt lgkmcnt(4)
	v_mfma_f32_16x16x32_bf16 v[100:103], v[202:205], v[226:229], v[100:103]
	v_mfma_f32_16x16x32_bf16 v[92:95], v[206:209], v[226:229], v[92:95]
	v_mfma_f32_16x16x32_bf16 v[96:99], v[210:213], v[226:229], v[96:99]
	v_mfma_f32_16x16x32_bf16 v[88:91], v[214:217], v[226:229], v[88:91]
	ds_read_b128 v[246:249], v7 offset:23552
	s_waitcnt lgkmcnt(4)
	v_mfma_f32_16x16x32_bf16 v[84:87], v[202:205], v[230:233], v[84:87]
	v_mfma_f32_16x16x32_bf16 v[76:79], v[206:209], v[230:233], v[76:79]
	v_mfma_f32_16x16x32_bf16 v[80:83], v[210:213], v[230:233], v[80:83]
	v_mfma_f32_16x16x32_bf16 v[72:75], v[214:217], v[230:233], v[72:75]
	s_waitcnt vmcnt(0) lgkmcnt(0)
	s_barrier
; template <int EPI> ...
;     ...
;       for (int t0_ = 0; t0_ < nt - 2; t0_ += 2) {
;         if constexpr (EPI == EPI_M0) {
;           if (t0_ == 8) {
;             int tid_s = tid;
;             asm volatile("" : "+v"(tid_s));
;             const int wid = tid_s >> 6, lane = tid_s & 63, wr = wid >> 2, wc = wid & 3, fr = lane & 15, fq = lane >> 4;
;             char* wsn = shm + 131072 + wid * 4096;
;             u16* sout = p.hbuf() + (long)(pm * 256 + wr * 128 + (lane >> 3)) * DM + pn * 256 + wc * 64 + (lane & 7) * 8;
; #pragma unroll
;             for (int qd = 0; qd < 4; ++qd) {
; #pragma unroll
;               for (int mm = 0; mm < 2; ++mm)
; #pragma unroll
;                 for (int n = 0; n < 4; ++n) {
;                   const f32x4 v = acc[qd * 2 + mm][n];
;                   u32x2 o = {pack2(v[0], v[1]), pack2(v[2], v[3])};
;                   *(u32x2*)(wsn + (mm * 16 + fr) * 128 + (((n * 2 + (fq >> 1)) ^ (fr & 7)) << 4) + (fq & 1) * 8) = o;
;                 }
;               asm volatile("s_waitcnt lgkmcnt(0)" ::: "memory");
; #pragma unroll
;               for (int i = 0; i < 4; ++i) {
;                 const u32x4 d = *(const u32x4*)(wsn + (i * 8 + (lane >> 3)) * 128 + (((lane & 7) ^ ((lane >> 3) & 7)) << 4));
;                 *(u32x4*)(sout + (long)(qd * 32 + i * 8) * DM) = d;
;               }
;               asm volatile("s_waitcnt lgkmcnt(0)" ::: "memory");
;             }
;           }
;         }
;         int t = t0_;
;         asm volatile("" : "+s"(t));
;         LDB8(B0, 0, 0); SCHED8; LDA8(At, 0, 0); STAGE_A(1, 1, Ab, t + 1);
;         WAIT_L(8); BAR8; WAIT_L(0); MMA8(0, 0, At, B0); BAR8; SCHED8;
;         LDB8(B1, 0, 1); STAGE_Bm(0, 0, Bb, t + 2);
;         BAR8; WAIT_L(0); MMA8(0, 1, At, B1); BAR8;
;         LDA8(At, 0, 1); STAGE_A(0, 0, Ab, t + 2);
;         BAR8; WAIT_L(0); MMA8(1, 0, At, B0); BAR8; SCHED8;
;         STAGE_Bm(0, 1, Bb, t + 2);
;         WAIT_V(6); BAR8; MMA8(1, 1, At, B1); BAR8;
;         LDB8(B0, 1, 0); SCHED8; LDA8(At, 1, 0); STAGE_A(0, 1, Ab, t + 2);
;         WAIT_L(8); BAR8; WAIT_L(0); MMA8(0, 0, At, B0); BAR8; SCHED8;
;         LDB8(B1, 1, 1); STAGE_Bm(1, 0, Bb, t + 3);
;         BAR8; WAIT_L(0); MMA8(0, 1, At, B1); BAR8;
;         LDA8(At, 1, 1); STAGE_A(1, 0, Ab, t + 3);
;         BAR8; WAIT_L(0); MMA8(1, 0, At, B0); BAR8; SCHED8;
;         STAGE_Bm(1, 1, Bb, t + 3);
	v_mfma_f32_16x16x32_bf16 v[68:71], v[202:205], v[234:237], v[68:71]
	v_mfma_f32_16x16x32_bf16 v[64:67], v[206:209], v[234:237], v[64:67]
	v_mfma_f32_16x16x32_bf16 v[60:63], v[210:213], v[234:237], v[60:63]
	v_mfma_f32_16x16x32_bf16 v[56:59], v[214:217], v[234:237], v[56:59]
	ds_read_b128 v[186:189], v181 offset:32768
	ds_read_b128 v[190:193], v181 offset:34816
	ds_read_b128 v[218:221], v180
	s_mov_b32 m0, s96
	v_lshl_add_u64 v[178:179], v[170:171], 0, s[22:23]
	global_load_lds_dwordx4 v[178:179], off
	s_waitcnt lgkmcnt(5)
	v_mfma_f32_16x16x32_bf16 v[52:55], v[202:205], v[238:241], v[52:55]
	v_mfma_f32_16x16x32_bf16 v[48:51], v[206:209], v[238:241], v[48:51]
	v_mfma_f32_16x16x32_bf16 v[44:47], v[210:213], v[238:241], v[44:47]
	v_mfma_f32_16x16x32_bf16 v[40:43], v[214:217], v[238:241], v[40:43]
	ds_read_b128 v[194:197], v181 offset:49152
	ds_read_b128 v[198:201], v181 offset:51200
	ds_read_b128 v[222:225], v180 offset:2048
	s_add_i32 m0, s96, 0x2000
	v_lshl_add_u64 v[178:179], v[170:171], 0, s[22:23]
	v_lshl_add_u64 v[178:179], v[178:179], 0, s[62:63]
	global_load_lds_dwordx4 v[178:179], off
	s_waitcnt lgkmcnt(7)
	v_mfma_f32_16x16x32_bf16 v[36:39], v[202:205], v[242:245], v[36:39]
	v_mfma_f32_16x16x32_bf16 v[32:35], v[206:209], v[242:245], v[32:35]
	v_mfma_f32_16x16x32_bf16 v[28:31], v[210:213], v[242:245], v[28:31]
	v_mfma_f32_16x16x32_bf16 v[24:27], v[214:217], v[242:245], v[24:27]
	ds_read_b128 v[226:229], v180 offset:4096
	ds_read_b128 v[230:233], v180 offset:6144
	s_add_i32 m0, s96, 0x4000
	v_lshl_add_u64 v[178:179], v[174:175], 0, s[22:23]
	global_load_lds_dwordx4 v[178:179], off
	s_waitcnt lgkmcnt(8)
	v_mfma_f32_16x16x32_bf16 v[20:23], v[202:205], v[246:249], v[20:23]
	v_mfma_f32_16x16x32_bf16 v[16:19], v[206:209], v[246:249], v[16:19]
	v_mfma_f32_16x16x32_bf16 v[12:15], v[210:213], v[246:249], v[12:15]
	v_mfma_f32_16x16x32_bf16 v[8:11], v[214:217], v[246:249], v[8:11]
	ds_read_b128 v[234:237], v180 offset:16384
	s_add_i32 m0, s96, 0x6000
	v_lshl_add_u64 v[178:179], v[174:175], 0, s[22:23]
	v_lshl_add_u64 v[178:179], v[178:179], 0, s[62:63]
	global_load_lds_dwordx4 v[178:179], off
	s_mov_b32 s24, 0
.Lp6_loop:
	s_waitcnt lgkmcnt(4)
	v_mfma_f32_16x16x32_bf16 v[132:135], v[186:189], v[218:221], v[132:135]
	v_mfma_f32_16x16x32_bf16 v[124:127], v[190:193], v[218:221], v[124:127]
	v_mfma_f32_16x16x32_bf16 v[128:131], v[194:197], v[218:221], v[128:131]
	v_mfma_f32_16x16x32_bf16 v[120:123], v[198:201], v[218:221], v[120:123]
	ds_read_b128 v[238:241], v180 offset:18432
	ds_read_b128 v[202:205], v181 offset:33792
	s_add_i32 m0, s96, 0x8000
	v_lshl_add_u64 v[178:179], v[172:173], 0, s[22:23]
	global_load_lds_dwordx4 v[178:179], off
	s_waitcnt lgkmcnt(5)
	v_mfma_f32_16x16x32_bf16 v[116:119], v[186:189], v[222:225], v[116:119]
	v_mfma_f32_16x16x32_bf16 v[108:111], v[190:193], v[222:225], v[108:111]
	v_mfma_f32_16x16x32_bf16 v[112:115], v[194:197], v[222:225], v[112:115]
	v_mfma_f32_16x16x32_bf16 v[104:107], v[198:201], v[222:225], v[104:107]
	ds_read_b128 v[242:245], v180 offset:20480
	ds_read_b128 v[206:209], v181 offset:35840
	s_add_i32 m0, s96, 0xa000
	v_lshl_add_u64 v[178:179], v[172:173], 0, s[22:23]
	v_lshl_add_u64 v[178:179], v[178:179], 0, s[62:63]
	global_load_lds_dwordx4 v[178:179], off
	s_waitcnt lgkmcnt(6)
	v_mfma_f32_16x16x32_bf16 v[100:103], v[186:189], v[226:229], v[100:103]
	v_mfma_f32_16x16x32_bf16 v[92:95], v[190:193], v[226:229], v[92:95]
	v_mfma_f32_16x16x32_bf16 v[96:99], v[194:197], v[226:229], v[96:99]
	v_mfma_f32_16x16x32_bf16 v[88:91], v[198:201], v[226:229], v[88:91]
	ds_read_b128 v[246:249], v180 offset:22528
	ds_read_b128 v[210:213], v181 offset:50176
	s_add_i32 m0, s96, 0xc000
	v_lshl_add_u64 v[178:179], v[176:177], 0, s[22:23]
	global_load_lds_dwordx4 v[178:179], off
	s_waitcnt lgkmcnt(7)
	v_mfma_f32_16x16x32_bf16 v[84:87], v[186:189], v[230:233], v[84:87]
	v_mfma_f32_16x16x32_bf16 v[76:79], v[190:193], v[230:233], v[76:79]
	v_mfma_f32_16x16x32_bf16 v[80:83], v[194:197], v[230:233], v[80:83]
	v_mfma_f32_16x16x32_bf16 v[72:75], v[198:201], v[230:233], v[72:75]
	ds_read_b128 v[218:221], v180 offset:1024
	ds_read_b128 v[214:217], v181 offset:52224
	s_add_i32 m0, s96, 0xe000
	v_lshl_add_u64 v[178:179], v[176:177], 0, s[22:23]
	v_lshl_add_u64 v[178:179], v[178:179], 0, s[62:63]
	global_load_lds_dwordx4 v[178:179], off
	s_add_u32 s22, s22, 0x80
	s_waitcnt lgkmcnt(8)
	v_mfma_f32_16x16x32_bf16 v[68:71], v[186:189], v[234:237], v[68:71]
	v_mfma_f32_16x16x32_bf16 v[64:67], v[190:193], v[234:237], v[64:67]
	v_mfma_f32_16x16x32_bf16 v[60:63], v[194:197], v[234:237], v[60:63]
	v_mfma_f32_16x16x32_bf16 v[56:59], v[198:201], v[234:237], v[56:59]
	ds_read_b128 v[222:225], v180 offset:3072
	s_waitcnt lgkmcnt(8)
	v_mfma_f32_16x16x32_bf16 v[52:55], v[186:189], v[238:241], v[52:55]
	v_mfma_f32_16x16x32_bf16 v[48:51], v[190:193], v[238:241], v[48:51]
	v_mfma_f32_16x16x32_bf16 v[44:47], v[194:197], v[238:241], v[44:47]
	v_mfma_f32_16x16x32_bf16 v[40:43], v[198:201], v[238:241], v[40:43]
	ds_read_b128 v[226:229], v180 offset:5120
	s_waitcnt lgkmcnt(7)
	v_mfma_f32_16x16x32_bf16 v[36:39], v[186:189], v[242:245], v[36:39]
	v_mfma_f32_16x16x32_bf16 v[32:35], v[190:193], v[242:245], v[32:35]
	v_mfma_f32_16x16x32_bf16 v[28:31], v[194:197], v[242:245], v[28:31]
	v_mfma_f32_16x16x32_bf16 v[24:27], v[198:201], v[242:245], v[24:27]
	ds_read_b128 v[230:233], v180 offset:7168
	s_waitcnt lgkmcnt(6)
	v_mfma_f32_16x16x32_bf16 v[20:23], v[186:189], v[246:249], v[20:23]
	v_mfma_f32_16x16x32_bf16 v[16:19], v[190:193], v[246:249], v[16:19]
	v_mfma_f32_16x16x32_bf16 v[12:15], v[194:197], v[246:249], v[12:15]
	v_mfma_f32_16x16x32_bf16 v[8:11], v[198:201], v[246:249], v[8:11]
	ds_read_b128 v[234:237], v180 offset:17408
	s_waitcnt lgkmcnt(4)
; template <int EPI> ...
;     ...
;       for (int t0_ = 0; t0_ < nt - 2; t0_ += 2) {
;         if constexpr (EPI == EPI_M0) {
;           if (t0_ == 8) {
;             int tid_s = tid;
;             asm volatile("" : "+v"(tid_s));
;             const int wid = tid_s >> 6, lane = tid_s & 63, wr = wid >> 2, wc = wid & 3, fr = lane & 15, fq = lane >> 4;
;             char* wsn = shm + 131072 + wid * 4096;
;             u16* sout = p.hbuf() + (long)(pm * 256 + wr * 128 + (lane >> 3)) * DM + pn * 256 + wc * 64 + (lane & 7) * 8;
; #pragma unroll
;             for (int qd = 0; qd < 4; ++qd) {
; #pragma unroll
;               for (int mm = 0; mm < 2; ++mm)
; #pragma unroll
;                 for (int n = 0; n < 4; ++n) {
;                   const f32x4 v = acc[qd * 2 + mm][n];
;                   u32x2 o = {pack2(v[0], v[1]), pack2(v[2], v[3])};
;                   *(u32x2*)(wsn + (mm * 16 + fr) * 128 + (((n * 2 + (fq >> 1)) ^ (fr & 7)) << 4) + (fq & 1) * 8) = o;
;                 }
;               asm volatile("s_waitcnt lgkmcnt(0)" ::: "memory");
; #pragma unroll
;               for (int i = 0; i < 4; ++i) {
;                 const u32x4 d = *(const u32x4*)(wsn + (i * 8 + (lane >> 3)) * 128 + (((lane & 7) ^ ((lane >> 3) & 7)) << 4));
;                 *(u32x4*)(sout + (long)(qd * 32 + i * 8) * DM) = d;
;               }
;               asm volatile("s_waitcnt lgkmcnt(0)" ::: "memory");
;             }
;           }
;         }
;         int t = t0_;
;         asm volatile("" : "+s"(t));
;         LDB8(B0, 0, 0); SCHED8; LDA8(At, 0, 0); STAGE_A(1, 1, Ab, t + 1);
;         WAIT_L(8); BAR8; WAIT_L(0); MMA8(0, 0, At, B0); BAR8; SCHED8;
;         LDB8(B1, 0, 1); STAGE_Bm(0, 0, Bb, t + 2);
;         BAR8; WAIT_L(0); MMA8(0, 1, At, B1); BAR8;
;         LDA8(At, 0, 1); STAGE_A(0, 0, Ab, t + 2);
;         BAR8; WAIT_L(0); MMA8(1, 0, At, B0); BAR8; SCHED8;
;         STAGE_Bm(0, 1, Bb, t + 2);
;         WAIT_V(6); BAR8; MMA8(1, 1, At, B1); BAR8;
;         LDB8(B0, 1, 0); SCHED8; LDA8(At, 1, 0); STAGE_A(0, 1, Ab, t + 2);
;         WAIT_L(8); BAR8; WAIT_L(0); MMA8(0, 0, At, B0); BAR8; SCHED8;
;         LDB8(B1, 1, 1); STAGE_Bm(1, 0, Bb, t + 3);
;         BAR8; WAIT_L(0); MMA8(0, 1, At, B1); BAR8;
;         LDA8(At, 1, 1); STAGE_A(1, 0, Ab, t + 3);
;         BAR8; WAIT_L(0); MMA8(1, 0, At, B0); BAR8; SCHED8;
;         STAGE_Bm(1, 1, Bb, t + 3);
	v_mfma_f32_16x16x32_bf16 v[132:135], v[202:205], v[218:221], v[132:135]
	v_mfma_f32_16x16x32_bf16 v[124:127], v[206:209], v[218:221], v[124:127]
	v_mfma_f32_16x16x32_bf16 v[128:131], v[210:213], v[218:221], v[128:131]
	v_mfma_f32_16x16x32_bf16 v[120:123], v[214:217], v[218:221], v[120:123]
	ds_read_b128 v[238:241], v180 offset:19456
	s_waitcnt lgkmcnt(4)
	v_mfma_f32_16x16x32_bf16 v[116:119], v[202:205], v[222:225], v[116:119]
	v_mfma_f32_16x16x32_bf16 v[108:111], v[206:209], v[222:225], v[108:111]
	v_mfma_f32_16x16x32_bf16 v[112:115], v[210:213], v[222:225], v[112:115]
	v_mfma_f32_16x16x32_bf16 v[104:107], v[214:217], v[222:225], v[104:107]
	ds_read_b128 v[242:245], v180 offset:21504
	s_waitcnt lgkmcnt(4)
	v_mfma_f32_16x16x32_bf16 v[100:103], v[202:205], v[226:229], v[100:103]
	v_mfma_f32_16x16x32_bf16 v[92:95], v[206:209], v[226:229], v[92:95]
	v_mfma_f32_16x16x32_bf16 v[96:99], v[210:213], v[226:229], v[96:99]
	v_mfma_f32_16x16x32_bf16 v[88:91], v[214:217], v[226:229], v[88:91]
	ds_read_b128 v[246:249], v180 offset:23552
	s_waitcnt lgkmcnt(4)
	v_mfma_f32_16x16x32_bf16 v[84:87], v[202:205], v[230:233], v[84:87]
	v_mfma_f32_16x16x32_bf16 v[76:79], v[206:209], v[230:233], v[76:79]
	v_mfma_f32_16x16x32_bf16 v[80:83], v[210:213], v[230:233], v[80:83]
	v_mfma_f32_16x16x32_bf16 v[72:75], v[214:217], v[230:233], v[72:75]
	s_waitcnt vmcnt(0) lgkmcnt(0)
	s_barrier
	v_mfma_f32_16x16x32_bf16 v[68:71], v[202:205], v[234:237], v[68:71]
	v_mfma_f32_16x16x32_bf16 v[64:67], v[206:209], v[234:237], v[64:67]
	v_mfma_f32_16x16x32_bf16 v[60:63], v[210:213], v[234:237], v[60:63]
	v_mfma_f32_16x16x32_bf16 v[56:59], v[214:217], v[234:237], v[56:59]
	ds_read_b128 v[186:189], v153 offset:32768
	ds_read_b128 v[190:193], v153 offset:34816
	ds_read_b128 v[218:221], v7
	s_add_i32 m0, s96, 0x10000
	v_lshl_add_u64 v[178:179], v[170:171], 0, s[22:23]
	global_load_lds_dwordx4 v[178:179], off
	s_waitcnt lgkmcnt(5)
	v_mfma_f32_16x16x32_bf16 v[52:55], v[202:205], v[238:241], v[52:55]
	v_mfma_f32_16x16x32_bf16 v[48:51], v[206:209], v[238:241], v[48:51]
	v_mfma_f32_16x16x32_bf16 v[44:47], v[210:213], v[238:241], v[44:47]
	v_mfma_f32_16x16x32_bf16 v[40:43], v[214:217], v[238:241], v[40:43]
	ds_read_b128 v[194:197], v153 offset:49152
	ds_read_b128 v[198:201], v153 offset:51200
	ds_read_b128 v[222:225], v7 offset:2048
	s_add_i32 m0, s96, 0x12000
	v_lshl_add_u64 v[178:179], v[170:171], 0, s[22:23]
	v_lshl_add_u64 v[178:179], v[178:179], 0, s[62:63]
	global_load_lds_dwordx4 v[178:179], off
	s_waitcnt lgkmcnt(7)
	v_mfma_f32_16x16x32_bf16 v[36:39], v[202:205], v[242:245], v[36:39]
	v_mfma_f32_16x16x32_bf16 v[32:35], v[206:209], v[242:245], v[32:35]
	v_mfma_f32_16x16x32_bf16 v[28:31], v[210:213], v[242:245], v[28:31]
	v_mfma_f32_16x16x32_bf16 v[24:27], v[214:217], v[242:245], v[24:27]
	ds_read_b128 v[226:229], v7 offset:4096
	ds_read_b128 v[230:233], v7 offset:6144
	s_add_i32 m0, s96, 0x14000
	v_lshl_add_u64 v[178:179], v[174:175], 0, s[22:23]
	global_load_lds_dwordx4 v[178:179], off
	s_waitcnt lgkmcnt(8)
	v_mfma_f32_16x16x32_bf16 v[20:23], v[202:205], v[246:249], v[20:23]
	v_mfma_f32_16x16x32_bf16 v[16:19], v[206:209], v[246:249], v[16:19]
	v_mfma_f32_16x16x32_bf16 v[12:15], v[210:213], v[246:249], v[12:15]
	v_mfma_f32_16x16x32_bf16 v[8:11], v[214:217], v[246:249], v[8:11]
	ds_read_b128 v[234:237], v7 offset:16384
	s_add_i32 m0, s96, 0x16000
	v_lshl_add_u64 v[178:179], v[174:175], 0, s[22:23]
	v_lshl_add_u64 v[178:179], v[178:179], 0, s[62:63]
	global_load_lds_dwordx4 v[178:179], off
	s_waitcnt lgkmcnt(4)
	v_mfma_f32_16x16x32_bf16 v[132:135], v[186:189], v[218:221], v[132:135]
	v_mfma_f32_16x16x32_bf16 v[124:127], v[190:193], v[218:221], v[124:127]
	v_mfma_f32_16x16x32_bf16 v[128:131], v[194:197], v[218:221], v[128:131]
	v_mfma_f32_16x16x32_bf16 v[120:123], v[198:201], v[218:221], v[120:123]
	ds_read_b128 v[238:241], v7 offset:18432
	ds_read_b128 v[202:205], v153 offset:33792
	s_add_i32 m0, s96, 0x18000
	v_lshl_add_u64 v[178:179], v[172:173], 0, s[22:23]
	global_load_lds_dwordx4 v[178:179], off
	s_waitcnt lgkmcnt(5)
	v_mfma_f32_16x16x32_bf16 v[116:119], v[186:189], v[222:225], v[116:119]
	v_mfma_f32_16x16x32_bf16 v[108:111], v[190:193], v[222:225], v[108:111]
	v_mfma_f32_16x16x32_bf16 v[112:115], v[194:197], v[222:225], v[112:115]
	v_mfma_f32_16x16x32_bf16 v[104:107], v[198:201], v[222:225], v[104:107]
	ds_read_b128 v[242:245], v7 offset:20480
	ds_read_b128 v[206:209], v153 offset:35840
	s_add_i32 m0, s96, 0x1a000
	v_lshl_add_u64 v[178:179], v[172:173], 0, s[22:23]
	v_lshl_add_u64 v[178:179], v[178:179], 0, s[62:63]
	global_load_lds_dwordx4 v[178:179], off
	s_waitcnt lgkmcnt(6)
	v_mfma_f32_16x16x32_bf16 v[100:103], v[186:189], v[226:229], v[100:103]
	v_mfma_f32_16x16x32_bf16 v[92:95], v[190:193], v[226:229], v[92:95]
	v_mfma_f32_16x16x32_bf16 v[96:99], v[194:197], v[226:229], v[96:99]
	v_mfma_f32_16x16x32_bf16 v[88:91], v[198:201], v[226:229], v[88:91]
	ds_read_b128 v[246:249], v7 offset:22528
	ds_read_b128 v[210:213], v153 offset:50176
	s_add_i32 m0, s96, 0x1c000
	v_lshl_add_u64 v[178:179], v[176:177], 0, s[22:23]
	global_load_lds_dwordx4 v[178:179], off
	s_waitcnt lgkmcnt(7)
	v_mfma_f32_16x16x32_bf16 v[84:87], v[186:189], v[230:233], v[84:87]
	v_mfma_f32_16x16x32_bf16 v[76:79], v[190:193], v[230:233], v[76:79]
	v_mfma_f32_16x16x32_bf16 v[80:83], v[194:197], v[230:233], v[80:83]
	v_mfma_f32_16x16x32_bf16 v[72:75], v[198:201], v[230:233], v[72:75]
	ds_read_b128 v[218:221], v7 offset:1024
	ds_read_b128 v[214:217], v153 offset:52224
	s_add_i32 m0, s96, 0x1e000
	v_lshl_add_u64 v[178:179], v[176:177], 0, s[22:23]
	v_lshl_add_u64 v[178:179], v[178:179], 0, s[62:63]
	global_load_lds_dwordx4 v[178:179], off
	s_add_u32 s22, s22, 0x80
	s_waitcnt lgkmcnt(8)
; template <int EPI> ...
;     ...
;       for (int t0_ = 0; t0_ < nt - 2; t0_ += 2) {
;         if constexpr (EPI == EPI_M0) {
;           if (t0_ == 8) {
;             int tid_s = tid;
;             asm volatile("" : "+v"(tid_s));
;             const int wid = tid_s >> 6, lane = tid_s & 63, wr = wid >> 2, wc = wid & 3, fr = lane & 15, fq = lane >> 4;
;             char* wsn = shm + 131072 + wid * 4096;
;             u16* sout = p.hbuf() + (long)(pm * 256 + wr * 128 + (lane >> 3)) * DM + pn * 256 + wc * 64 + (lane & 7) * 8;
; #pragma unroll
;             for (int qd = 0; qd < 4; ++qd) {
; #pragma unroll
;               for (int mm = 0; mm < 2; ++mm)
; #pragma unroll
;                 for (int n = 0; n < 4; ++n) {
;                   const f32x4 v = acc[qd * 2 + mm][n];
;                   u32x2 o = {pack2(v[0], v[1]), pack2(v[2], v[3])};
;                   *(u32x2*)(wsn + (mm * 16 + fr) * 128 + (((n * 2 + (fq >> 1)) ^ (fr & 7)) << 4) + (fq & 1) * 8) = o;
;                 }
;               asm volatile("s_waitcnt lgkmcnt(0)" ::: "memory");
; #pragma unroll
;               for (int i = 0; i < 4; ++i) {
;                 const u32x4 d = *(const u32x4*)(wsn + (i * 8 + (lane >> 3)) * 128 + (((lane & 7) ^ ((lane >> 3) & 7)) << 4));
;                 *(u32x4*)(sout + (long)(qd * 32 + i * 8) * DM) = d;
;               }
;               asm volatile("s_waitcnt lgkmcnt(0)" ::: "memory");
;             }
;           }
;         }
;         int t = t0_;
;         asm volatile("" : "+s"(t));
;         LDB8(B0, 0, 0); SCHED8; LDA8(At, 0, 0); STAGE_A(1, 1, Ab, t + 1);
;         WAIT_L(8); BAR8; WAIT_L(0); MMA8(0, 0, At, B0); BAR8; SCHED8;
;         LDB8(B1, 0, 1); STAGE_Bm(0, 0, Bb, t + 2);
;         BAR8; WAIT_L(0); MMA8(0, 1, At, B1); BAR8;
;         LDA8(At, 0, 1); STAGE_A(0, 0, Ab, t + 2);
;         BAR8; WAIT_L(0); MMA8(1, 0, At, B0); BAR8; SCHED8;
;         STAGE_Bm(0, 1, Bb, t + 2);
;         WAIT_V(6); BAR8; MMA8(1, 1, At, B1); BAR8;
;         LDB8(B0, 1, 0); SCHED8; LDA8(At, 1, 0); STAGE_A(0, 1, Ab, t + 2);
;         WAIT_L(8); BAR8; WAIT_L(0); MMA8(0, 0, At, B0); BAR8; SCHED8;
;         LDB8(B1, 1, 1); STAGE_Bm(1, 0, Bb, t + 3);
;         BAR8; WAIT_L(0); MMA8(0, 1, At, B1); BAR8;
;         LDA8(At, 1, 1); STAGE_A(1, 0, Ab, t + 3);
;         BAR8; WAIT_L(0); MMA8(1, 0, At, B0); BAR8; SCHED8;
;         STAGE_Bm(1, 1, Bb, t + 3);
	v_mfma_f32_16x16x32_bf16 v[68:71], v[186:189], v[234:237], v[68:71]
	v_mfma_f32_16x16x32_bf16 v[64:67], v[190:193], v[234:237], v[64:67]
	v_mfma_f32_16x16x32_bf16 v[60:63], v[194:197], v[234:237], v[60:63]
	v_mfma_f32_16x16x32_bf16 v[56:59], v[198:201], v[234:237], v[56:59]
	ds_read_b128 v[222:225], v7 offset:3072
	s_waitcnt lgkmcnt(8)
	v_mfma_f32_16x16x32_bf16 v[52:55], v[186:189], v[238:241], v[52:55]
	v_mfma_f32_16x16x32_bf16 v[48:51], v[190:193], v[238:241], v[48:51]
	v_mfma_f32_16x16x32_bf16 v[44:47], v[194:197], v[238:241], v[44:47]
	v_mfma_f32_16x16x32_bf16 v[40:43], v[198:201], v[238:241], v[40:43]
	ds_read_b128 v[226:229], v7 offset:5120
	s_waitcnt lgkmcnt(7)
	v_mfma_f32_16x16x32_bf16 v[36:39], v[186:189], v[242:245], v[36:39]
	v_mfma_f32_16x16x32_bf16 v[32:35], v[190:193], v[242:245], v[32:35]
	v_mfma_f32_16x16x32_bf16 v[28:31], v[194:197], v[242:245], v[28:31]
	v_mfma_f32_16x16x32_bf16 v[24:27], v[198:201], v[242:245], v[24:27]
	ds_read_b128 v[230:233], v7 offset:7168
	s_waitcnt lgkmcnt(6)
	v_mfma_f32_16x16x32_bf16 v[20:23], v[186:189], v[246:249], v[20:23]
	v_mfma_f32_16x16x32_bf16 v[16:19], v[190:193], v[246:249], v[16:19]
	v_mfma_f32_16x16x32_bf16 v[12:15], v[194:197], v[246:249], v[12:15]
	v_mfma_f32_16x16x32_bf16 v[8:11], v[198:201], v[246:249], v[8:11]
	ds_read_b128 v[234:237], v7 offset:17408
	s_waitcnt lgkmcnt(4)
	v_mfma_f32_16x16x32_bf16 v[132:135], v[202:205], v[218:221], v[132:135]
	v_mfma_f32_16x16x32_bf16 v[124:127], v[206:209], v[218:221], v[124:127]
	v_mfma_f32_16x16x32_bf16 v[128:131], v[210:213], v[218:221], v[128:131]
	v_mfma_f32_16x16x32_bf16 v[120:123], v[214:217], v[218:221], v[120:123]
	ds_read_b128 v[238:241], v7 offset:19456
	s_waitcnt lgkmcnt(4)
	v_mfma_f32_16x16x32_bf16 v[116:119], v[202:205], v[222:225], v[116:119]
	v_mfma_f32_16x16x32_bf16 v[108:111], v[206:209], v[222:225], v[108:111]
	v_mfma_f32_16x16x32_bf16 v[112:115], v[210:213], v[222:225], v[112:115]
	v_mfma_f32_16x16x32_bf16 v[104:107], v[214:217], v[222:225], v[104:107]
	ds_read_b128 v[242:245], v7 offset:21504
	s_waitcnt lgkmcnt(4)
	v_mfma_f32_16x16x32_bf16 v[100:103], v[202:205], v[226:229], v[100:103]
	v_mfma_f32_16x16x32_bf16 v[92:95], v[206:209], v[226:229], v[92:95]
	v_mfma_f32_16x16x32_bf16 v[96:99], v[210:213], v[226:229], v[96:99]
	v_mfma_f32_16x16x32_bf16 v[88:91], v[214:217], v[226:229], v[88:91]
	ds_read_b128 v[246:249], v7 offset:23552
	s_waitcnt lgkmcnt(4)
	v_mfma_f32_16x16x32_bf16 v[84:87], v[202:205], v[230:233], v[84:87]
	v_mfma_f32_16x16x32_bf16 v[76:79], v[206:209], v[230:233], v[76:79]
	v_mfma_f32_16x16x32_bf16 v[80:83], v[210:213], v[230:233], v[80:83]
	v_mfma_f32_16x16x32_bf16 v[72:75], v[214:217], v[230:233], v[72:75]
	s_waitcnt vmcnt(0) lgkmcnt(0)
	s_barrier
	v_mfma_f32_16x16x32_bf16 v[68:71], v[202:205], v[234:237], v[68:71]
	v_mfma_f32_16x16x32_bf16 v[64:67], v[206:209], v[234:237], v[64:67]
	v_mfma_f32_16x16x32_bf16 v[60:63], v[210:213], v[234:237], v[60:63]
	v_mfma_f32_16x16x32_bf16 v[56:59], v[214:217], v[234:237], v[56:59]
	ds_read_b128 v[186:189], v181 offset:32768
	ds_read_b128 v[190:193], v181 offset:34816
	ds_read_b128 v[218:221], v180
	s_cmp_eq_u32 s24, 6
	s_cbranch_scc1 .Lp6_sk1
	s_mov_b32 m0, s96
	v_lshl_add_u64 v[178:179], v[170:171], 0, s[22:23]
	global_load_lds_dwordx4 v[178:179], off
.Lp6_sk1:
	s_waitcnt lgkmcnt(5)
	v_mfma_f32_16x16x32_bf16 v[52:55], v[202:205], v[238:241], v[52:55]
	v_mfma_f32_16x16x32_bf16 v[48:51], v[206:209], v[238:241], v[48:51]
	v_mfma_f32_16x16x32_bf16 v[44:47], v[210:213], v[238:241], v[44:47]
	v_mfma_f32_16x16x32_bf16 v[40:43], v[214:217], v[238:241], v[40:43]
	ds_read_b128 v[194:197], v181 offset:49152
	ds_read_b128 v[198:201], v181 offset:51200
	ds_read_b128 v[222:225], v180 offset:2048
	s_cmp_eq_u32 s24, 6
	s_cbranch_scc1 .Lp6_sk2
	s_add_i32 m0, s96, 0x2000
	v_lshl_add_u64 v[178:179], v[170:171], 0, s[22:23]
	v_lshl_add_u64 v[178:179], v[178:179], 0, s[62:63]
	global_load_lds_dwordx4 v[178:179], off
.Lp6_sk2:
	s_waitcnt lgkmcnt(7)
	v_mfma_f32_16x16x32_bf16 v[36:39], v[202:205], v[242:245], v[36:39]
	v_mfma_f32_16x16x32_bf16 v[32:35], v[206:209], v[242:245], v[32:35]
	v_mfma_f32_16x16x32_bf16 v[28:31], v[210:213], v[242:245], v[28:31]
	v_mfma_f32_16x16x32_bf16 v[24:27], v[214:217], v[242:245], v[24:27]
	ds_read_b128 v[226:229], v180 offset:4096
	ds_read_b128 v[230:233], v180 offset:6144
	s_cmp_eq_u32 s24, 6
	s_cbranch_scc1 .Lp6_sk3
	s_add_i32 m0, s96, 0x4000
	v_lshl_add_u64 v[178:179], v[174:175], 0, s[22:23]
	global_load_lds_dwordx4 v[178:179], off
.Lp6_sk3:
	s_waitcnt lgkmcnt(8)
	v_mfma_f32_16x16x32_bf16 v[20:23], v[202:205], v[246:249], v[20:23]
	v_mfma_f32_16x16x32_bf16 v[16:19], v[206:209], v[246:249], v[16:19]
	v_mfma_f32_16x16x32_bf16 v[12:15], v[210:213], v[246:249], v[12:15]
	v_mfma_f32_16x16x32_bf16 v[8:11], v[214:217], v[246:249], v[8:11]
	ds_read_b128 v[234:237], v180 offset:16384
	s_cmp_eq_u32 s24, 6
	s_cbranch_scc1 .Lp6_sk4
	s_add_i32 m0, s96, 0x6000
	v_lshl_add_u64 v[178:179], v[174:175], 0, s[22:23]
	v_lshl_add_u64 v[178:179], v[178:179], 0, s[62:63]
	global_load_lds_dwordx4 v[178:179], off
; #define WAIT_V(n) asm volatile("s_waitcnt vmcnt(%0)" ::"n"(n) : "memory")
; #define GLDS_STAGE(Ap, Bp, buf, kt)                                                                                  \
;   do {                                                                                                               \
;     STAGE_Bm(0, 0, Bp, 0); STAGE_A(0, 0, Ap, 0); STAGE_Bm(0, 1, Bp, 0); STAGE_A(0, 1, Ap, 0);                        \
;   } while (0)
; #define LDA8(dst, b, h)                                                                                              \
;   _Pragma("unroll") for (int m_ = 0; m_ < 4; ++m_) _Pragma("unroll") for (int k_ = 0; k_ < 2; ++k_)                  \
;     dst[m_][k_] = *(const bf16x8*)(shm + SLOT_A(b, h) + abase8 + m_ * 2048 + k_ * 1024)
; #define LDB8(dst, b, h)                                                                                              \
;   _Pragma("unroll") for (int n_ = 0; n_ < 2; ++n_) _Pragma("unroll") for (int k_ = 0; k_ < 2; ++k_)                  \
;     dst[n_][k_] = *(const bf16x8*)(shm + SLOT_B(b, h) + bbase8 + n_ * 2048 + k_ * 1024)
; #define WAIT_L(n) asm volatile("s_waitcnt lgkmcnt(%0)" ::"n"(n) : "memory")
; #define BAR8 __builtin_amdgcn_s_barrier()
; template <int EPI> ...
;     ...
;       {
;         LDB8(B0, 0, 0); LDA8(At, 0, 0); STAGE_A(1, 1, Ab, nt - 1);
;         BAR8; WAIT_L(0); MMA8(0, 0, At, B0); BAR8;
;         LDB8(B1, 0, 1); BAR8; WAIT_L(0); MMA8(0, 1, At, B1); BAR8;
;         LDA8(At, 0, 1); WAIT_V(4); BAR8; WAIT_L(0); MMA8(1, 0, At, B0); MMA8(1, 1, At, B1); BAR8;
;       }
;       {
;         LDB8(B0, 1, 0); LDA8(At, 1, 0); WAIT_V(2); BAR8; WAIT_L(0); MMA8(0, 0, At, B0); BAR8;
;         LDB8(B1, 1, 1); WAIT_V(0); BAR8; WAIT_L(0); MMA8(0, 1, At, B1); BAR8;
;         LDA8(At, 1, 1); BAR8; WAIT_L(0); MMA8(1, 0, At, B0); MMA8(1, 1, At, B1); BAR8;
;       }
;       if (wr == 0) BAR8;
;     }
;     float rs[8];
;     if constexpr (EPI == EPI_PROJ || EPI == EPI_RELU2) {
;       unsigned long long sqc[8];
; #pragma unroll
;       for (int m = 0; m < 8; ++m) sqc[m] = ssq_in[pm * 256 + wr * 128 + fr + m * 16];
; #pragma unroll
;       for (int m = 0; m < 8; ++m) rs[m] = rsqrtf((float)sqc[m] * SSQ_UNFIX + 1e-6f);
;       if (have2) GLDS_STAGE(Ab2, Bb2, 0, 0);
.Lp6_sk4:
	s_add_u32 s24, s24, 1
	s_cmp_lt_u32 s24, 7
	s_cbranch_scc1 .Lp6_loop
	s_waitcnt lgkmcnt(4)
	v_mfma_f32_16x16x32_bf16 v[132:135], v[186:189], v[218:221], v[132:135]
	v_mfma_f32_16x16x32_bf16 v[124:127], v[190:193], v[218:221], v[124:127]
	v_mfma_f32_16x16x32_bf16 v[128:131], v[194:197], v[218:221], v[128:131]
	v_mfma_f32_16x16x32_bf16 v[120:123], v[198:201], v[218:221], v[120:123]
	s_lshl_b32 s22, s93, 8
	v_add_u32_e32 v136, s22, v154
	v_ashrrev_i32_e32 v137, 31, v136
	v_lshl_add_u64 v[136:137], v[136:137], 3, s[12:13]
	global_load_dwordx2 v[150:151], v[136:137], off
	global_load_dwordx2 v[148:149], v[136:137], off offset:128
	global_load_dwordx2 v[146:147], v[136:137], off offset:256
	global_load_dwordx2 v[144:145], v[136:137], off offset:384
	global_load_dwordx2 v[142:143], v[136:137], off offset:512
	global_load_dwordx2 v[140:141], v[136:137], off offset:640
	global_load_dwordx2 v[138:139], v[136:137], off offset:768
	s_nop 0
	global_load_dwordx2 v[136:137], v[136:137], off offset:896
	ds_read_b128 v[238:241], v180 offset:18432
	ds_read_b128 v[202:205], v181 offset:33792
	s_waitcnt lgkmcnt(5)
	v_mfma_f32_16x16x32_bf16 v[116:119], v[186:189], v[222:225], v[116:119]
	v_mfma_f32_16x16x32_bf16 v[108:111], v[190:193], v[222:225], v[108:111]
	v_mfma_f32_16x16x32_bf16 v[112:115], v[194:197], v[222:225], v[112:115]
	v_mfma_f32_16x16x32_bf16 v[104:107], v[198:201], v[222:225], v[104:107]
	ds_read_b128 v[242:245], v180 offset:20480
	ds_read_b128 v[206:209], v181 offset:35840
	s_waitcnt lgkmcnt(6)
	v_mfma_f32_16x16x32_bf16 v[100:103], v[186:189], v[226:229], v[100:103]
	v_mfma_f32_16x16x32_bf16 v[92:95], v[190:193], v[226:229], v[92:95]
	v_mfma_f32_16x16x32_bf16 v[96:99], v[194:197], v[226:229], v[96:99]
	v_mfma_f32_16x16x32_bf16 v[88:91], v[198:201], v[226:229], v[88:91]
	ds_read_b128 v[246:249], v180 offset:22528
	ds_read_b128 v[210:213], v181 offset:50176
	s_waitcnt lgkmcnt(7)
	v_mfma_f32_16x16x32_bf16 v[84:87], v[186:189], v[230:233], v[84:87]
	v_mfma_f32_16x16x32_bf16 v[76:79], v[190:193], v[230:233], v[76:79]
	v_mfma_f32_16x16x32_bf16 v[80:83], v[194:197], v[230:233], v[80:83]
	v_mfma_f32_16x16x32_bf16 v[72:75], v[198:201], v[230:233], v[72:75]
	ds_read_b128 v[218:221], v180 offset:1024
	ds_read_b128 v[214:217], v181 offset:52224
	s_waitcnt lgkmcnt(8)
	v_mfma_f32_16x16x32_bf16 v[68:71], v[186:189], v[234:237], v[68:71]
	v_mfma_f32_16x16x32_bf16 v[64:67], v[190:193], v[234:237], v[64:67]
	v_mfma_f32_16x16x32_bf16 v[60:63], v[194:197], v[234:237], v[60:63]
	v_mfma_f32_16x16x32_bf16 v[56:59], v[198:201], v[234:237], v[56:59]
	ds_read_b128 v[222:225], v180 offset:3072
	s_waitcnt lgkmcnt(8)
	v_mfma_f32_16x16x32_bf16 v[52:55], v[186:189], v[238:241], v[52:55]
	v_mfma_f32_16x16x32_bf16 v[48:51], v[190:193], v[238:241], v[48:51]
	v_mfma_f32_16x16x32_bf16 v[44:47], v[194:197], v[238:241], v[44:47]
	v_mfma_f32_16x16x32_bf16 v[40:43], v[198:201], v[238:241], v[40:43]
	ds_read_b128 v[226:229], v180 offset:5120
	s_waitcnt lgkmcnt(7)
	v_mfma_f32_16x16x32_bf16 v[36:39], v[186:189], v[242:245], v[36:39]
	v_mfma_f32_16x16x32_bf16 v[32:35], v[190:193], v[242:245], v[32:35]
	v_mfma_f32_16x16x32_bf16 v[28:31], v[194:197], v[242:245], v[28:31]
	v_mfma_f32_16x16x32_bf16 v[24:27], v[198:201], v[242:245], v[24:27]
	ds_read_b128 v[230:233], v180 offset:7168
	s_waitcnt lgkmcnt(6)
	v_mfma_f32_16x16x32_bf16 v[20:23], v[186:189], v[246:249], v[20:23]
	v_mfma_f32_16x16x32_bf16 v[16:19], v[190:193], v[246:249], v[16:19]
	v_mfma_f32_16x16x32_bf16 v[12:15], v[194:197], v[246:249], v[12:15]
	v_mfma_f32_16x16x32_bf16 v[8:11], v[198:201], v[246:249], v[8:11]
	ds_read_b128 v[234:237], v180 offset:17408
	s_waitcnt lgkmcnt(4)
	v_mfma_f32_16x16x32_bf16 v[132:135], v[202:205], v[218:221], v[132:135]
	v_mfma_f32_16x16x32_bf16 v[124:127], v[206:209], v[218:221], v[124:127]
	v_mfma_f32_16x16x32_bf16 v[128:131], v[210:213], v[218:221], v[128:131]
	v_mfma_f32_16x16x32_bf16 v[120:123], v[214:217], v[218:221], v[120:123]
	ds_read_b128 v[238:241], v180 offset:19456
	s_waitcnt lgkmcnt(4)
	v_mfma_f32_16x16x32_bf16 v[116:119], v[202:205], v[222:225], v[116:119]
	v_mfma_f32_16x16x32_bf16 v[108:111], v[206:209], v[222:225], v[108:111]
	v_mfma_f32_16x16x32_bf16 v[112:115], v[210:213], v[222:225], v[112:115]
	v_mfma_f32_16x16x32_bf16 v[104:107], v[214:217], v[222:225], v[104:107]
	ds_read_b128 v[242:245], v180 offset:21504
	s_waitcnt lgkmcnt(4)
	v_mfma_f32_16x16x32_bf16 v[100:103], v[202:205], v[226:229], v[100:103]
	v_mfma_f32_16x16x32_bf16 v[92:95], v[206:209], v[226:229], v[92:95]
	v_mfma_f32_16x16x32_bf16 v[96:99], v[210:213], v[226:229], v[96:99]
	v_mfma_f32_16x16x32_bf16 v[88:91], v[214:217], v[226:229], v[88:91]
	ds_read_b128 v[246:249], v180 offset:23552
	s_waitcnt lgkmcnt(4)
	v_mfma_f32_16x16x32_bf16 v[84:87], v[202:205], v[230:233], v[84:87]
	v_mfma_f32_16x16x32_bf16 v[76:79], v[206:209], v[230:233], v[76:79]
	v_mfma_f32_16x16x32_bf16 v[80:83], v[210:213], v[230:233], v[80:83]
	v_mfma_f32_16x16x32_bf16 v[72:75], v[214:217], v[230:233], v[72:75]
	s_waitcnt vmcnt(0) lgkmcnt(0)
	s_barrier
; #define WAIT_V(n) asm volatile("s_waitcnt vmcnt(%0)" ::"n"(n) : "memory")
; #define GLDS_STAGE(Ap, Bp, buf, kt)                                                                                  \
;   do {                                                                                                               \
;     STAGE_Bm(0, 0, Bp, 0); STAGE_A(0, 0, Ap, 0); STAGE_Bm(0, 1, Bp, 0); STAGE_A(0, 1, Ap, 0);                        \
;   } while (0)
; #define LDA8(dst, b, h)                                                                                              \
;   _Pragma("unroll") for (int m_ = 0; m_ < 4; ++m_) _Pragma("unroll") for (int k_ = 0; k_ < 2; ++k_)                  \
;     dst[m_][k_] = *(const bf16x8*)(shm + SLOT_A(b, h) + abase8 + m_ * 2048 + k_ * 1024)
; #define LDB8(dst, b, h)                                                                                              \
;   _Pragma("unroll") for (int n_ = 0; n_ < 2; ++n_) _Pragma("unroll") for (int k_ = 0; k_ < 2; ++k_)                  \
;     dst[n_][k_] = *(const bf16x8*)(shm + SLOT_B(b, h) + bbase8 + n_ * 2048 + k_ * 1024)
; #define WAIT_L(n) asm volatile("s_waitcnt lgkmcnt(%0)" ::"n"(n) : "memory")
; #define BAR8 __builtin_amdgcn_s_barrier()
; template <int EPI> ...
;     ...
;       {
;         LDB8(B0, 1, 0); LDA8(At, 1, 0); WAIT_V(2); BAR8; WAIT_L(0); MMA8(0, 0, At, B0); BAR8;
;         LDB8(B1, 1, 1); WAIT_V(0); BAR8; WAIT_L(0); MMA8(0, 1, At, B1); BAR8;
;         LDA8(At, 1, 1); BAR8; WAIT_L(0); MMA8(1, 0, At, B0); MMA8(1, 1, At, B1); BAR8;
;       }
;       if (wr == 0) BAR8;
;     }
;     float rs[8];
;     if constexpr (EPI == EPI_PROJ || EPI == EPI_RELU2) {
;       unsigned long long sqc[8];
; #pragma unroll
;       for (int m = 0; m < 8; ++m) sqc[m] = ssq_in[pm * 256 + wr * 128 + fr + m * 16];
; #pragma unroll
;       for (int m = 0; m < 8; ++m) rs[m] = rsqrtf((float)sqc[m] * SSQ_UNFIX + 1e-6f);
;       if (have2) GLDS_STAGE(Ab2, Bb2, 0, 0);
	v_mfma_f32_16x16x32_bf16 v[68:71], v[202:205], v[234:237], v[68:71]
	v_mfma_f32_16x16x32_bf16 v[64:67], v[206:209], v[234:237], v[64:67]
	v_mfma_f32_16x16x32_bf16 v[60:63], v[210:213], v[234:237], v[60:63]
	v_mfma_f32_16x16x32_bf16 v[56:59], v[214:217], v[234:237], v[56:59]
	ds_read_b128 v[186:189], v153 offset:32768
	ds_read_b128 v[190:193], v153 offset:34816
	ds_read_b128 v[218:221], v7
	s_waitcnt lgkmcnt(5)
	v_mfma_f32_16x16x32_bf16 v[52:55], v[202:205], v[238:241], v[52:55]
	v_mfma_f32_16x16x32_bf16 v[48:51], v[206:209], v[238:241], v[48:51]
	v_mfma_f32_16x16x32_bf16 v[44:47], v[210:213], v[238:241], v[44:47]
	v_mfma_f32_16x16x32_bf16 v[40:43], v[214:217], v[238:241], v[40:43]
	ds_read_b128 v[194:197], v153 offset:49152
	ds_read_b128 v[198:201], v153 offset:51200
	ds_read_b128 v[222:225], v7 offset:2048
	s_waitcnt lgkmcnt(7)
	v_mfma_f32_16x16x32_bf16 v[36:39], v[202:205], v[242:245], v[36:39]
	v_mfma_f32_16x16x32_bf16 v[32:35], v[206:209], v[242:245], v[32:35]
	v_mfma_f32_16x16x32_bf16 v[28:31], v[210:213], v[242:245], v[28:31]
	v_mfma_f32_16x16x32_bf16 v[24:27], v[214:217], v[242:245], v[24:27]
	ds_read_b128 v[226:229], v7 offset:4096
	ds_read_b128 v[230:233], v7 offset:6144
	s_waitcnt lgkmcnt(8)
	v_mfma_f32_16x16x32_bf16 v[20:23], v[202:205], v[246:249], v[20:23]
	v_mfma_f32_16x16x32_bf16 v[16:19], v[206:209], v[246:249], v[16:19]
	v_mfma_f32_16x16x32_bf16 v[12:15], v[210:213], v[246:249], v[12:15]
	v_mfma_f32_16x16x32_bf16 v[8:11], v[214:217], v[246:249], v[8:11]
	ds_read_b128 v[234:237], v7 offset:16384
	s_waitcnt lgkmcnt(0)
	s_barrier
	s_andn2_b64 vcc, exec, s[20:21]
	s_cbranch_vccnz .LBB0_674
	s_mov_b32 m0, s59
	v_lshl_add_u64 v[156:157], s[16:17], 0, v[4:5]
	global_load_lds_dwordx4 v[156:157], off
	v_lshl_add_u64 v[158:159], v[156:157], 0, s[62:63]
	s_mov_b32 m0, s65
	s_mov_b64 s[20:21], 0x20000
	global_load_lds_dwordx4 v[158:159], off
	v_lshl_add_u64 v[158:159], s[14:15], 0, v[0:1]
	s_mov_b32 m0, s96
	v_lshl_add_u64 v[170:171], v[158:159], 0, s[62:63]
	global_load_lds_dwordx4 v[158:159], off
	s_mov_b32 m0, s70
	s_nop 0
	global_load_lds_dwordx4 v[170:171], off
	v_lshl_add_u64 v[170:171], v[156:157], 0, s[44:45]
	s_mov_b32 m0, s71
	v_lshl_add_u64 v[156:157], v[156:157], 0, s[46:47]
	global_load_lds_dwordx4 v[170:171], off
	s_mov_b32 m0, s72
	s_nop 0
	global_load_lds_dwordx4 v[156:157], off
	v_lshl_add_u64 v[156:157], v[158:159], 0, s[20:21]
	s_mov_b32 m0, s73
	s_nop 0
	global_load_lds_dwordx4 v[156:157], off
	v_lshl_add_u64 v[156:157], v[158:159], 0, s[48:49]
	s_mov_b32 m0, s74
	s_nop 0
	global_load_lds_dwordx4 v[156:157], off
	s_branch .LBB0_674
